# stick-breaking loop: plain packed f32 adds split into scalar adds (bit-identical)
# speedup vs baseline: 1.0075x; 1.0030x over previous
; template <int TYPE>
; DI void attn_item(KargPtr p, int b, int h, int qb, unsigned char* smem) {
;     ...
;                 float run = carry;
; #pragma unroll
;                 for (int g = 3; g >= 0; --g) {
;                     const float G = (lk1[4 * g] + lk1[4 * g + 1]) + (lk1[4 * g + 2] + lk1[4 * g + 3]);
;                     const float Gp = __shfl_xor(G, 32);
;                     const float base = run + (hh == 0 ? Gp : 0.f);
;                     const float e3 = base, e2 = e3 + lk1[4 * g + 3], e1 = e2 + lk1[4 * g + 2], e0 = e1 + lk1[4 * g + 1];
;                     s1[4 * g + 3] = fexp2(s1[4 * g + 3] + e3); s1[4 * g + 2] = fexp2(s1[4 * g + 2] + e2);
;                     s1[4 * g + 1] = fexp2(s1[4 * g + 1] + e1); s1[4 * g] = fexp2(s1[4 * g] + e0);
;                     run += G + Gp;
;                 }
; #pragma unroll
;                 for (int g = 3; g >= 0; --g) {
;                     const float G = (lk0[4 * g] + lk0[4 * g + 1]) + (lk0[4 * g + 2] + lk0[4 * g + 3]);
;                     const float Gp = __shfl_xor(G, 32);
;                     const float base = run + (hh == 0 ? Gp : 0.f);
;                     const float e3 = base, e2 = e3 + lk0[4 * g + 3], e1 = e2 + lk0[4 * g + 2], e0 = e1 + lk0[4 * g + 1];
;                     s0[4 * g + 3] = fexp2(s0[4 * g + 3] + e3); s0[4 * g + 2] = fexp2(s0[4 * g + 2] + e2);
;                     s0[4 * g + 1] = fexp2(s0[4 * g + 1] + e1); s0[4 * g] = fexp2(s0[4 * g] + e0);
;                     run += G + Gp;
;                 }
;                 carry = run;
;             }
; #pragma unroll
;             for (int s2 = 0; s2 < 2; ++s2) {
;                 unsigned pk0[4], pk1[4];
; #pragma unroll
;                 for (int j = 0; j < 4; ++j) { pk0[j] = pack_bf16(s0[8 * s2 + 2 * j], s0[8 * s2 + 2 * j + 1]); pk1[j] = pack_bf16(s1[8 * s2 + 2 * j], s1[8 * s2 + 2 * j + 1]); }
;                 const uint4 u0 = make_uint4(pk0[0], pk0[1], pk0[2], pk0[3]), u1 = make_uint4(pk1[0], pk1[1], pk1[2], pk1[3]);
;                 const bf16x8 pf0 = __builtin_bit_cast(bf16x8, u0), pf1 = __builtin_bit_cast(bf16x8, u1);
;                 const bf16x8 v00 = *(const bf16x8*)(vb + r * VROWB + (16 * s2 + 8 * hh) * 2);
;                 const bf16x8 v01 = *(const bf16x8*)(vb + (32 + r) * VROWB + (16 * s2 + 8 * hh) * 2);
;                 const bf16x8 v10 = *(const bf16x8*)(vb + r * VROWB + (32 + 16 * s2 + 8 * hh) * 2);
.LBB0_575:
	s_or_b64 exec, exec, s[90:91]
	v_and_b32_e32 v67, 64, v205
	v_xor_b32_e32 v66, 32, v205
	v_add_u32_e32 v67, 64, v67
	v_cmp_lt_i32_e32 vcc, v66, v67
	v_add_f32_e32 v70, v60, v65
	v_mov_b32_e32 v67, v62
	v_cndmask_b32_e32 v66, v205, v66, vcc
	v_lshlrev_b32_e32 v68, 2, v66
	v_add_f32_e32 v66, v64, v63
	v_mov_b32_e32 v71, v59
	v_add_f32_e32 v66, v66, v70
	v_add_f32_e32 v67, v67, v71
	ds_bpermute_b32 v72, v68, v66
	v_add_f32_e32 v73, v58, v61
	v_mov_b32_e32 v74, v52
	v_mov_b32_e32 v75, v53
	s_waitcnt lgkmcnt(0)
	v_add_f32_e32 v66, v66, v72
	v_add_f32_e32 v67, v67, v73
	ds_bpermute_b32 v165, v68, v67
	v_cndmask_b32_e64 v62, 0, v72, s[4:5]
	v_add_f32_e32 v62, v164, v62
	v_add_f32_e32 v64, v65, v62
	v_add_f32_e32 v65, v60, v64
	v_add_f32_e32 v69, v63, v65
	v_add_f32_e32 v63, v195, v65
	s_waitcnt lgkmcnt(0)
	v_cndmask_b32_e64 v65, 0, v165, s[4:5]
	v_add_f32_e32 v70, v164, v66
	v_add_f32_e32 v71, v165, v67
	v_mov_b32_e32 v72, v56
	v_add_f32_e32 v65, v70, v65
	v_add_f32_e32 v66, v61, v65
	v_add_f32_e32 v58, v58, v66
	v_add_f32_e32 v59, v59, v58
	v_add_f32_e32 v58, v191, v58
	v_add_f32_e32 v61, v193, v65
	v_add_f32_e32 v65, v192, v66
	v_exp_f32_e32 v66, v58
	v_add_f32_e32 v58, v190, v59
	v_exp_f32_e32 v67, v58
	v_pk_add_f32 v[58:59], v[70:71], v[70:71] op_sel:[0,1] op_sel_hi:[1,0]
	v_mov_b32_e32 v70, v55
	v_mov_b32_e32 v71, v54
	v_mov_b32_e32 v73, v57
	v_add_f32_e32 v70, v70, v72
	v_add_f32_e32 v71, v71, v73
	v_add_f32_e32 v60, v197, v62
	v_add_f32_e32 v56, v70, v71
	ds_bpermute_b32 v59, v68, v56
	v_add_f32_e32 v62, v196, v64
	v_add_f32_e32 v64, v194, v69
	v_exp_f32_e32 v60, v60
	v_exp_f32_e32 v62, v62
	s_waitcnt lgkmcnt(0)
	v_cndmask_b32_e64 v69, 0, v59, s[4:5]
	v_add_f32_e32 v69, v58, v69
	v_add_f32_e32 v57, v57, v69
	v_add_f32_e32 v54, v54, v57
	v_add_f32_e32 v55, v55, v54
	v_add_f32_e32 v54, v187, v54
	v_exp_f32_e32 v71, v54
	v_add_f32_e32 v54, v186, v55
	v_exp_f32_e32 v72, v54
	v_mov_b32_e32 v54, v51
	v_mov_b32_e32 v55, v50
	v_add_f32_e32 v54, v54, v74
	v_add_f32_e32 v55, v55, v75
	v_add_f32_e32 v57, v188, v57
	v_pk_add_f32 v[54:55], v[54:55], v[54:55] op_sel:[0,1] op_sel_hi:[1,0]
	ds_bpermute_b32 v52, v68, v54
	v_exp_f32_e32 v70, v57
	v_add_f32_e32 v56, v56, v59
	v_mov_b32_e32 v59, v14
	v_mov_b32_e32 v57, v49
	s_waitcnt lgkmcnt(0)
	v_cndmask_b32_e64 v55, 0, v52, s[4:5]
	v_add_f32_e32 v56, v58, v56
	v_add_f32_e32 v57, v59, v57
	v_add_f32_e32 v69, v189, v69
	v_add_f32_e32 v55, v56, v55
	v_add_f32_e32 v53, v53, v55
	v_add_f32_e32 v58, v50, v53
	v_add_f32_e32 v59, v51, v58
	v_add_f32_e32 v51, v184, v53
	v_add_f32_e32 v53, v181, v58
	v_exp_f32_e32 v58, v53
	v_add_f32_e32 v53, v180, v59
	v_add_f32_e32 v50, v185, v55
	v_exp_f32_e32 v59, v53
	v_mov_b32_e32 v55, v48
	v_mov_b32_e32 v53, v15
	v_add_f32_e32 v52, v54, v52
	v_add_f32_e32 v53, v55, v53
	v_exp_f32_e32 v69, v69
	v_add_f32_e32 v54, v52, v56
	v_add_f32_e32 v55, v53, v57
	ds_bpermute_b32 v56, v68, v55
	v_mov_b32_e32 v57, v11
	v_exp_f32_e32 v50, v50
	v_exp_f32_e32 v51, v51
	v_exp_f32_e32 v63, v63
	s_waitcnt lgkmcnt(0)
	v_cndmask_b32_e64 v48, 0, v56, s[4:5]
	v_add_f32_e32 v48, v54, v48
	v_add_f32_e32 v49, v49, v48
	v_add_f32_e32 v14, v14, v49
	v_add_f32_e32 v15, v15, v14
	v_add_f32_e32 v14, v179, v14
	v_exp_f32_e32 v52, v14
	v_add_f32_e32 v14, v178, v15
	v_exp_f32_e32 v53, v14
	v_add_f32_e32 v14, v55, v56
	v_add_f32_e32 v14, v54, v14
	v_mov_b32_e32 v54, v13
	v_mov_b32_e32 v55, v10
	v_mov_b32_e32 v56, v12
	v_add_f32_e32 v54, v54, v56
	v_add_f32_e32 v55, v55, v57
	v_add_f32_e32 v48, v183, v48
	v_add_f32_e32 v12, v54, v55
	ds_bpermute_b32 v15, v68, v12
	v_mov_b32_e32 v55, v7
	v_add_f32_e32 v49, v182, v49
	v_exp_f32_e32 v48, v48
	v_exp_f32_e32 v49, v49
	s_waitcnt lgkmcnt(0)
	v_cndmask_b32_e64 v54, 0, v15, s[4:5]
	v_add_f32_e32 v54, v14, v54
	v_add_f32_e32 v11, v11, v54
	v_add_f32_e32 v10, v10, v11
	v_add_f32_e32 v13, v13, v10
	v_add_f32_e32 v10, v175, v10
	v_add_f32_e32 v54, v177, v54
	v_exp_f32_e32 v138, v10
	v_add_f32_e32 v10, v174, v13
	v_exp_f32_e32 v80, v54
	v_exp_f32_e32 v139, v10
	v_add_f32_e32 v10, v12, v15
	v_mov_b32_e32 v12, v9
	v_mov_b32_e32 v13, v6
	v_mov_b32_e32 v54, v8
	v_add_f32_e32 v12, v12, v54
	v_add_f32_e32 v13, v13, v55
	v_add_f32_e32 v11, v176, v11
	v_pk_add_f32 v[12:13], v[12:13], v[12:13] op_sel:[0,1] op_sel_hi:[1,0]
	ds_bpermute_b32 v8, v68, v12
	v_exp_f32_e32 v81, v11
	v_mov_b32_e32 v15, v4
	v_mov_b32_e32 v11, v5
	v_add_f32_e32 v10, v14, v10
	v_add_f32_e32 v11, v15, v11
	s_waitcnt lgkmcnt(0)
	v_cndmask_b32_e64 v13, 0, v8, s[4:5]
	v_add_f32_e32 v13, v10, v13
	v_add_f32_e32 v7, v7, v13
	v_add_f32_e32 v6, v6, v7
	v_add_f32_e32 v9, v9, v6
	v_add_f32_e32 v13, v173, v13
	v_add_f32_e32 v6, v171, v6
	v_exp_f32_e32 v14, v13
	v_add_f32_e32 v7, v172, v7
	v_exp_f32_e32 v54, v6
	v_add_f32_e32 v6, v170, v9
	v_mov_b32_e32 v13, v0
	v_mov_b32_e32 v9, v1
	v_exp_f32_e32 v15, v7
	v_exp_f32_e32 v55, v6
	v_add_f32_e32 v6, v12, v8
	v_add_f32_e32 v7, v13, v9
	v_exp_f32_e32 v64, v64
	v_add_f32_e32 v6, v6, v10
	v_add_f32_e32 v7, v7, v11
	ds_bpermute_b32 v0, v68, v7
	v_cvt_pk_bf16_f32 v10, v72, v71
	v_cvt_pk_bf16_f32 v11, v70, v69
	v_exp_f32_e32 v61, v61
	v_exp_f32_e32 v65, v65
	s_waitcnt lgkmcnt(0)
	v_cndmask_b32_e64 v8, 0, v0, s[4:5]
	v_add_f32_e32 v8, v6, v8
	v_add_f32_e32 v5, v5, v8
	v_add_f32_e32 v4, v4, v5
	v_add_f32_e32 v1, v1, v4
	v_add_f32_e32 v8, v169, v8
	v_add_f32_e32 v5, v168, v5
	v_add_f32_e32 v4, v167, v4
	v_add_f32_e32 v1, v166, v1
	v_exp_f32_e32 v9, v8
	v_exp_f32_e32 v5, v5
	v_exp_f32_e32 v4, v4
	v_exp_f32_e32 v1, v1
	v_add_f32_e32 v0, v7, v0
	v_add_f32_e32 v164, v6, v0
	v_cvt_pk_bf16_f32 v6, v55, v54
	v_cvt_pk_bf16_f32 v7, v15, v14
	ds_read_b128 v[12:15], v224 offset:13824
	ds_read_b128 v[54:57], v224 offset:9280
	ds_read_b128 v[68:71], v224 offset:13888
	ds_read_b128 v[72:75], v224 offset:9216
	ds_read_b128 v[76:79], v224 offset:9248
	v_cvt_pk_bf16_f32 v4, v1, v4
	v_cvt_pk_bf16_f32 v5, v5, v9
	v_cvt_pk_bf16_f32 v8, v59, v58
	v_cvt_pk_bf16_f32 v9, v51, v50
	s_waitcnt lgkmcnt(1)
	v_mfma_f32_32x32x16_bf16 v[32:47], v[72:75], v[4:7], v[32:47]
	v_mfma_f32_32x32x16_bf16 v[16:31], v[12:15], v[4:7], v[16:31]
	v_cvt_pk_bf16_f32 v6, v53, v52
	v_cvt_pk_bf16_f32 v7, v49, v48
	v_cvt_pk_bf16_f32 v4, v139, v138
	v_cvt_pk_bf16_f32 v5, v81, v80
	v_mfma_f32_32x32x16_bf16 v[32:47], v[54:57], v[8:11], v[32:47]
	ds_read_b128 v[12:15], v224 offset:13856
	ds_read_b128 v[48:51], v224 offset:9312
	ds_read_b128 v[52:55], v224 offset:13920
	v_mfma_f32_32x32x16_bf16 v[16:31], v[68:71], v[8:11], v[16:31]
	v_cvt_pk_bf16_f32 v8, v67, v66
	v_cvt_pk_bf16_f32 v9, v65, v61
	v_cvt_pk_bf16_f32 v10, v64, v63
	v_cvt_pk_bf16_f32 v11, v62, v60
	s_waitcnt lgkmcnt(3)
	v_mfma_f32_32x32x16_bf16 v[32:47], v[76:79], v[4:7], v[32:47]
	s_waitcnt lgkmcnt(2)
	v_mfma_f32_32x32x16_bf16 v[16:31], v[12:15], v[4:7], v[16:31]
	s_waitcnt lgkmcnt(1)
	v_mfma_f32_32x32x16_bf16 v[32:47], v[48:51], v[8:11], v[32:47]
	s_waitcnt lgkmcnt(0)
	v_mfma_f32_32x32x16_bf16 v[16:31], v[52:55], v[8:11], v[16:31]

; template <int TYPE>
; DI void attn_item(KargPtr p, int b, int h, int qb, unsigned char* smem) {
;     ...
;                 float run = carry;
; #pragma unroll
;                 for (int g = 3; g >= 0; --g) {
;                     const float G = (lk1[4 * g] + lk1[4 * g + 1]) + (lk1[4 * g + 2] + lk1[4 * g + 3]);
;                     const float Gp = __shfl_xor(G, 32);
;                     const float base = run + (hh == 0 ? Gp : 0.f);
;                     const float e3 = base, e2 = e3 + lk1[4 * g + 3], e1 = e2 + lk1[4 * g + 2], e0 = e1 + lk1[4 * g + 1];
;                     s1[4 * g + 3] = fexp2(s1[4 * g + 3] + e3); s1[4 * g + 2] = fexp2(s1[4 * g + 2] + e2);
;                     s1[4 * g + 1] = fexp2(s1[4 * g + 1] + e1); s1[4 * g] = fexp2(s1[4 * g] + e0);
;                     run += G + Gp;
;                 }
; #pragma unroll
;                 for (int g = 3; g >= 0; --g) {
;                     const float G = (lk0[4 * g] + lk0[4 * g + 1]) + (lk0[4 * g + 2] + lk0[4 * g + 3]);
;                     const float Gp = __shfl_xor(G, 32);
;                     const float base = run + (hh == 0 ? Gp : 0.f);
;                     const float e3 = base, e2 = e3 + lk0[4 * g + 3], e1 = e2 + lk0[4 * g + 2], e0 = e1 + lk0[4 * g + 1];
;                     s0[4 * g + 3] = fexp2(s0[4 * g + 3] + e3); s0[4 * g + 2] = fexp2(s0[4 * g + 2] + e2);
;                     s0[4 * g + 1] = fexp2(s0[4 * g + 1] + e1); s0[4 * g] = fexp2(s0[4 * g] + e0);
;                     run += G + Gp;
;                 }
;                 carry = run;
;             }
; #pragma unroll
;             for (int s2 = 0; s2 < 2; ++s2) {
;                 unsigned pk0[4], pk1[4];
; #pragma unroll
;                 for (int j = 0; j < 4; ++j) { pk0[j] = pack_bf16(s0[8 * s2 + 2 * j], s0[8 * s2 + 2 * j + 1]); pk1[j] = pack_bf16(s1[8 * s2 + 2 * j], s1[8 * s2 + 2 * j + 1]); }
;                 const uint4 u0 = make_uint4(pk0[0], pk0[1], pk0[2], pk0[3]), u1 = make_uint4(pk1[0], pk1[1], pk1[2], pk1[3]);
;                 const bf16x8 pf0 = __builtin_bit_cast(bf16x8, u0), pf1 = __builtin_bit_cast(bf16x8, u1);
;                 const bf16x8 v00 = *(const bf16x8*)(vb + r * VROWB + (16 * s2 + 8 * hh) * 2);
;                 const bf16x8 v01 = *(const bf16x8*)(vb + (32 + r) * VROWB + (16 * s2 + 8 * hh) * 2);
;                 const bf16x8 v10 = *(const bf16x8*)(vb + r * VROWB + (32 + 16 * s2 + 8 * hh) * 2);
.LBB0_582:
	s_or_b64 exec, exec, s[90:91]
	v_and_b32_e32 v66, 64, v205
	v_xor_b32_e32 v64, 32, v205
	v_add_u32_e32 v66, 64, v66
	v_cmp_lt_i32_e32 vcc, v64, v66
	v_add_f32_e32 v66, v62, v63
	v_add_f32_e32 v70, v58, v65
	v_cndmask_b32_e32 v64, v205, v64, vcc
	v_mov_b32_e32 v67, v60
	v_mov_b32_e32 v71, v59
	v_lshlrev_b32_e32 v68, 2, v64
	v_add_f32_e32 v66, v66, v70
	v_add_f32_e32 v67, v67, v71
	ds_bpermute_b32 v72, v68, v66
	v_add_f32_e32 v73, v56, v61
	s_waitcnt lgkmcnt(0)
	v_cndmask_b32_e64 v60, 0, v72, s[4:5]
	v_add_f32_e32 v66, v66, v72
	v_add_f32_e32 v67, v67, v73
	v_add_f32_e32 v60, v164, v60
	ds_bpermute_b32 v165, v68, v67
	v_add_f32_e32 v62, v65, v60
	v_add_f32_e32 v58, v58, v62
	v_add_f32_e32 v64, v63, v58
	v_add_f32_e32 v58, v195, v58
	v_exp_f32_e32 v63, v58
	v_add_f32_e32 v58, v194, v64
	v_exp_f32_e32 v64, v58
	s_waitcnt lgkmcnt(0)
	v_cndmask_b32_e64 v58, 0, v165, s[4:5]
	v_add_f32_e32 v70, v164, v66
	v_add_f32_e32 v71, v165, v67
	v_mov_b32_e32 v72, v54
	v_add_f32_e32 v58, v70, v58
	v_add_f32_e32 v65, v61, v58
	v_add_f32_e32 v56, v56, v65
	v_add_f32_e32 v58, v193, v58
	v_add_f32_e32 v59, v59, v56
	v_exp_f32_e32 v61, v58
	v_add_f32_e32 v58, v192, v65
	v_add_f32_e32 v56, v191, v56
	v_exp_f32_e32 v65, v58
	v_exp_f32_e32 v66, v56
	v_add_f32_e32 v56, v190, v59
	v_pk_add_f32 v[58:59], v[70:71], v[70:71] op_sel:[0,1] op_sel_hi:[1,0]
	v_mov_b32_e32 v70, v55
	v_mov_b32_e32 v71, v52
	v_mov_b32_e32 v73, v57
	v_add_f32_e32 v70, v70, v72
	v_add_f32_e32 v71, v71, v73
	v_exp_f32_e32 v67, v56
	v_add_f32_e32 v54, v70, v71
	ds_bpermute_b32 v56, v68, v54
	v_mov_b32_e32 v72, v50
	v_mov_b32_e32 v73, v53
	v_add_f32_e32 v60, v197, v60
	v_add_f32_e32 v62, v196, v62
	s_waitcnt lgkmcnt(0)
	v_cndmask_b32_e64 v59, 0, v56, s[4:5]
	v_add_f32_e32 v59, v58, v59
	v_add_f32_e32 v57, v57, v59
	v_add_f32_e32 v70, v52, v57
	v_add_f32_e32 v55, v55, v70
	v_add_f32_e32 v55, v186, v55
	v_exp_f32_e32 v71, v55
	v_add_f32_e32 v56, v54, v56
	v_mov_b32_e32 v54, v51
	v_mov_b32_e32 v55, v48
	v_add_f32_e32 v54, v54, v72
	v_add_f32_e32 v55, v55, v73
	v_add_f32_e32 v57, v188, v57
	v_pk_add_f32 v[54:55], v[54:55], v[54:55] op_sel:[0,1] op_sel_hi:[1,0]
	ds_bpermute_b32 v50, v68, v54
	v_exp_f32_e32 v69, v57
	v_add_f32_e32 v57, v187, v70
	v_add_f32_e32 v52, v189, v59
	v_exp_f32_e32 v70, v57
	v_mov_b32_e32 v59, v14
	v_mov_b32_e32 v57, v49
	s_waitcnt lgkmcnt(0)
	v_cndmask_b32_e64 v55, 0, v50, s[4:5]
	v_add_f32_e32 v56, v58, v56
	v_add_f32_e32 v57, v59, v57
	v_exp_f32_e32 v52, v52
	v_add_f32_e32 v55, v56, v55
	v_add_f32_e32 v53, v53, v55
	v_add_f32_e32 v58, v48, v53
	v_add_f32_e32 v51, v51, v58
	v_add_f32_e32 v48, v185, v55
	v_add_f32_e32 v55, v181, v58
	v_add_f32_e32 v51, v180, v51
	v_exp_f32_e32 v58, v55
	v_exp_f32_e32 v59, v51
	v_mov_b32_e32 v55, v12
	v_mov_b32_e32 v51, v15
	v_add_f32_e32 v50, v54, v50
	v_add_f32_e32 v51, v55, v51
	v_add_f32_e32 v53, v184, v53
	v_add_f32_e32 v54, v50, v56
	v_add_f32_e32 v55, v51, v57
	ds_bpermute_b32 v12, v68, v55
	v_mov_b32_e32 v57, v11
	v_exp_f32_e32 v48, v48
	v_exp_f32_e32 v53, v53
	v_exp_f32_e32 v60, v60
	s_waitcnt lgkmcnt(0)
	v_cndmask_b32_e64 v50, 0, v12, s[4:5]
	v_add_f32_e32 v50, v54, v50
	v_add_f32_e32 v49, v49, v50
	v_add_f32_e32 v51, v14, v49
	v_add_f32_e32 v56, v15, v51
	v_add_f32_e32 v12, v55, v12
	v_add_f32_e32 v14, v183, v50
	v_add_f32_e32 v50, v178, v56
	v_add_f32_e32 v12, v54, v12
	v_mov_b32_e32 v54, v13
	v_mov_b32_e32 v55, v10
	v_mov_b32_e32 v56, v8
	v_add_f32_e32 v54, v54, v56
	v_add_f32_e32 v55, v55, v57
	v_add_f32_e32 v15, v182, v49
	v_add_f32_e32 v8, v54, v55
	v_add_f32_e32 v49, v179, v51
	ds_bpermute_b32 v51, v68, v8
	v_mov_b32_e32 v55, v6
	v_mov_b32_e32 v56, v4
	v_mov_b32_e32 v57, v7
	v_exp_f32_e32 v14, v14
	s_waitcnt lgkmcnt(0)
	v_cndmask_b32_e64 v54, 0, v51, s[4:5]
	v_add_f32_e32 v54, v12, v54
	v_add_f32_e32 v11, v11, v54
	v_add_f32_e32 v54, v177, v54
	v_add_f32_e32 v10, v10, v11
	v_exp_f32_e32 v80, v54
	v_mov_b32_e32 v54, v9
	v_add_f32_e32 v13, v13, v10
	v_add_f32_e32 v10, v175, v10
	v_add_f32_e32 v54, v54, v56
	v_add_f32_e32 v55, v55, v57
	v_exp_f32_e32 v138, v10
	v_add_f32_e32 v10, v174, v13
	v_pk_add_f32 v[54:55], v[54:55], v[54:55] op_sel:[0,1] op_sel_hi:[1,0]
	v_exp_f32_e32 v139, v10
	v_add_f32_e32 v10, v8, v51
	ds_bpermute_b32 v8, v68, v54
	v_add_f32_e32 v11, v176, v11
	v_exp_f32_e32 v81, v11
	v_mov_b32_e32 v13, v2
	v_mov_b32_e32 v11, v5
	s_waitcnt lgkmcnt(0)
	v_cndmask_b32_e64 v4, 0, v8, s[4:5]
	v_add_f32_e32 v10, v12, v10
	v_add_f32_e32 v11, v13, v11
	v_mov_b32_e32 v55, v0
	v_add_f32_e32 v4, v10, v4
	v_add_f32_e32 v7, v7, v4
	v_add_f32_e32 v4, v173, v4
	v_add_f32_e32 v6, v6, v7
	v_exp_f32_e32 v12, v4
	v_add_f32_e32 v4, v172, v7
	v_add_f32_e32 v9, v9, v6
	v_exp_f32_e32 v13, v4
	v_add_f32_e32 v4, v171, v6
	v_exp_f32_e32 v51, v4
	v_add_f32_e32 v4, v170, v9
	v_mov_b32_e32 v9, v1
	v_add_f32_e32 v6, v54, v8
	v_add_f32_e32 v7, v55, v9
	v_exp_f32_e32 v56, v4
	v_add_f32_e32 v6, v6, v10
	v_add_f32_e32 v7, v7, v11
	ds_bpermute_b32 v0, v68, v7
	v_cvt_pk_bf16_f32 v8, v59, v58
	v_cvt_pk_bf16_f32 v10, v71, v70
	v_cvt_pk_bf16_f32 v11, v69, v52
	v_exp_f32_e32 v15, v15
	s_waitcnt lgkmcnt(0)
	v_cndmask_b32_e64 v4, 0, v0, s[4:5]
	v_add_f32_e32 v4, v6, v4
	v_add_f32_e32 v5, v5, v4
	v_add_f32_e32 v4, v169, v4
	v_exp_f32_e32 v9, v4
	v_add_f32_e32 v4, v168, v5
	v_add_f32_e32 v2, v2, v5
	v_exp_f32_e32 v5, v4
	v_add_f32_e32 v1, v1, v2
	v_add_f32_e32 v2, v167, v2
	v_add_f32_e32 v1, v166, v1
	v_exp_f32_e32 v2, v2
	v_exp_f32_e32 v1, v1
	v_add_f32_e32 v0, v7, v0
	v_add_f32_e32 v164, v6, v0
	v_cvt_pk_bf16_f32 v5, v5, v9
	v_cvt_pk_bf16_f32 v9, v53, v48
	v_cvt_pk_bf16_f32 v6, v56, v51
	ds_read_b128 v[52:55], v224 offset:32512
	ds_read_b128 v[56:59], v224 offset:27968
	ds_read_b128 v[68:71], v224 offset:32576
	ds_read_b128 v[72:75], v224 offset:27904
	ds_read_b128 v[76:79], v224 offset:27936
	v_cvt_pk_bf16_f32 v4, v1, v2
	v_cvt_pk_bf16_f32 v7, v13, v12
	v_exp_f32_e32 v49, v49
	v_exp_f32_e32 v50, v50
	s_waitcnt lgkmcnt(1)
	v_mfma_f32_32x32x16_bf16 v[32:47], v[72:75], v[4:7], v[32:47]
	v_exp_f32_e32 v62, v62
	v_mfma_f32_32x32x16_bf16 v[16:31], v[52:55], v[4:7], v[16:31]
	v_cvt_pk_bf16_f32 v6, v50, v49
	v_cvt_pk_bf16_f32 v7, v15, v14
	ds_read_b128 v[12:15], v224 offset:32544
	ds_read_b128 v[48:51], v224 offset:28000
	ds_read_b128 v[52:55], v224 offset:32608
	v_cvt_pk_bf16_f32 v4, v139, v138
	v_cvt_pk_bf16_f32 v5, v81, v80
	v_mfma_f32_32x32x16_bf16 v[32:47], v[56:59], v[8:11], v[32:47]
	v_mfma_f32_32x32x16_bf16 v[16:31], v[68:71], v[8:11], v[16:31]
	v_cvt_pk_bf16_f32 v8, v67, v66
	v_cvt_pk_bf16_f32 v9, v65, v61
	v_cvt_pk_bf16_f32 v10, v64, v63
	v_cvt_pk_bf16_f32 v11, v62, v60
	s_waitcnt lgkmcnt(3)
	v_mfma_f32_32x32x16_bf16 v[32:47], v[76:79], v[4:7], v[32:47]
	s_waitcnt lgkmcnt(2)
	v_mfma_f32_32x32x16_bf16 v[16:31], v[12:15], v[4:7], v[16:31]
	s_waitcnt lgkmcnt(1)
	v_mfma_f32_32x32x16_bf16 v[32:47], v[48:51], v[8:11], v[32:47]
	s_waitcnt lgkmcnt(0)
	v_mfma_f32_32x32x16_bf16 v[16:31], v[52:55], v[8:11], v[16:31]
